# dilated attention output: 16 B stores via permlane16_swap pairing (on top of v47)
# baseline (speedup 1.0000x reference)
.LBB0_238:
	s_or_b64 exec, exec, s[44:45]
	s_nop 1
	v_mov_b32_e32 v2, v1
	s_nop 1
	v_permlane16_swap_b32_e32 v1, v2
	v_add_f32_e32 v1, v1, v2
	v_mov_b32_e32 v2, v1
	s_nop 1
	v_permlane32_swap_b32_e32 v1, v2
	v_add_f32_e32 v1, v1, v2
	v_div_scale_f32 v2, s[8:9], v1, v1, 1.0
	v_rcp_f32_e32 v3, v2
	s_ashr_i32 s23, s22, 31
	s_lshl_b64 s[8:9], s[22:23], 13
	s_or_b32 s8, s8, s64
	v_fma_f32 v36, -v2, v3, 1.0
	v_fmac_f32_e32 v3, v36, v3
	v_div_scale_f32 v36, vcc, 1.0, v1, 1.0
	v_mul_f32_e32 v37, v36, v3
	v_fma_f32 v38, -v2, v37, v36
	v_fmac_f32_e32 v37, v38, v3
	v_fma_f32 v2, -v2, v37, v36
	v_div_fmas_f32 v2, v2, v3, v37
	v_div_fixup_f32 v36, v2, v1, 1.0
	v_lshlrev_b64 v[2:3], s19, v[102:103]
	v_lshl_add_u64 v[2:3], s[8:9], 0, v[2:3]
	v_mov_b64_e32 v[38:39], s[42:43]
	v_mad_u64_u32 v[38:39], s[8:9], v2, s55, v[38:39]
	v_mov_b32_e32 v40, v39
	v_mad_u64_u32 v[40:41], s[8:9], v3, s55, v[40:41]
	v_mov_b32_e32 v39, v40
	v_lshl_add_u64 v[38:39], s[24:25], 1, v[38:39]
	v_mov_b32_e32 v101, v0
	v_pk_mul_f32 v[34:35], v[34:35], v[36:37] op_sel_hi:[1,0]
	v_pk_mul_f32 v[32:33], v[32:33], v[36:37] op_sel_hi:[1,0]
	v_pk_mul_f32 v[30:31], v[30:31], v[36:37] op_sel_hi:[1,0]
	v_pk_mul_f32 v[28:29], v[28:29], v[36:37] op_sel_hi:[1,0]
	v_pk_mul_f32 v[26:27], v[26:27], v[36:37] op_sel_hi:[1,0]
	v_pk_mul_f32 v[24:25], v[24:25], v[36:37] op_sel_hi:[1,0]
	v_pk_mul_f32 v[22:23], v[22:23], v[36:37] op_sel_hi:[1,0]
	v_pk_mul_f32 v[20:21], v[20:21], v[36:37] op_sel_hi:[1,0]
	v_pk_mul_f32 v[18:19], v[18:19], v[36:37] op_sel_hi:[1,0]
	v_pk_mul_f32 v[16:17], v[16:17], v[36:37] op_sel_hi:[1,0]
	v_pk_mul_f32 v[14:15], v[14:15], v[36:37] op_sel_hi:[1,0]
	v_pk_mul_f32 v[12:13], v[12:13], v[36:37] op_sel_hi:[1,0]
	v_pk_mul_f32 v[10:11], v[10:11], v[36:37] op_sel_hi:[1,0]
	v_pk_mul_f32 v[8:9], v[8:9], v[36:37] op_sel_hi:[1,0]
	v_pk_mul_f32 v[6:7], v[6:7], v[36:37] op_sel_hi:[1,0]
	v_pk_mul_f32 v[4:5], v[4:5], v[36:37] op_sel_hi:[1,0]
	v_lshl_add_u64 v[38:39], v[38:39], 0, v[100:101]
	v_bfe_u32 v36, v136, 4, 1
	v_mul_u32_u24_e32 v36, 24, v36
	v_mov_b32_e32 v37, 0
	v_lshl_add_u64 v[38:39], v[38:39], 0, v[36:37]
	v_cvt_pk_bf16_f32 v32, v32, v33
	v_cvt_pk_bf16_f32 v33, v34, v35
	v_cvt_pk_bf16_f32 v34, v28, v29
	v_cvt_pk_bf16_f32 v35, v30, v31
	v_cvt_pk_bf16_f32 v24, v24, v25
	v_cvt_pk_bf16_f32 v25, v26, v27
	v_cvt_pk_bf16_f32 v26, v20, v21
	v_cvt_pk_bf16_f32 v27, v22, v23
	v_cvt_pk_bf16_f32 v16, v16, v17
	v_cvt_pk_bf16_f32 v17, v18, v19
	v_cvt_pk_bf16_f32 v18, v12, v13
	v_cvt_pk_bf16_f32 v19, v14, v15
	v_cvt_pk_bf16_f32 v8, v8, v9
	v_cvt_pk_bf16_f32 v9, v10, v11
	v_cvt_pk_bf16_f32 v10, v4, v5
	v_cvt_pk_bf16_f32 v11, v6, v7
	s_barrier
	s_nop 1
	v_permlane16_swap_b32_e32 v32, v34
	v_permlane16_swap_b32_e32 v33, v35
	v_permlane16_swap_b32_e32 v24, v26
	v_permlane16_swap_b32_e32 v25, v27
	v_permlane16_swap_b32_e32 v16, v18
	v_permlane16_swap_b32_e32 v17, v19
	v_permlane16_swap_b32_e32 v8, v10
	v_permlane16_swap_b32_e32 v9, v11
	global_store_dwordx4 v[38:39], v[32:35], off
	global_store_dwordx4 v[38:39], v[24:27], off offset:64
	global_store_dwordx4 v[38:39], v[16:19], off offset:128
	global_store_dwordx4 v[38:39], v[8:11], off offset:192
	s_and_saveexec_b64 s[8:9], s[6:7]
	s_cbranch_execz .LBB0_221
	v_mov_b64_e32 v[4:5], s[12:13]
	v_log_f32_e32 v1, v1
	v_mad_u64_u32 v[4:5], s[22:23], v2, s56, v[4:5]
	v_mov_b32_e32 v2, v5
	v_mad_u64_u32 v[2:3], s[22:23], v3, s56, v[2:3]
	s_ashr_i32 s19, s18, 31
	v_mov_b32_e32 v5, v2
	v_add_f32_e32 v1, v122, v1
	v_lshl_add_u64 v[2:3], s[18:19], 2, v[4:5]
	global_store_dword v[2:3], v1, off
	s_branch .LBB0_221
